# phase 1: the 16 workgroups that compute the compress biases skip the rmsnorm rows; their 512 rows go one each to 128 other workgroups
# speedup vs baseline: 1.0060x; 1.0060x over previous
.LBB0_284:
	s_or_b64 exec, exec, s[6:7]
	s_and_b64 s[2:3], s[2:3], exec
	v_readlane_b32 s4, v251, 8
	v_readlane_b32 s2, v254, 30
	v_readlane_b32 s5, v251, 9
	v_readlane_b32 s3, v254, 31
	s_cselect_b32 s47, s5, s87
	s_cselect_b32 s46, s4, s86
	s_lshl_b32 s2, s2, 10
	s_mov_b32 s3, s77
	v_writelane_b32 v254, s2, 34
	v_mov_b32_e32 v0, v186
	v_readlane_b32 s6, v251, 10
	v_writelane_b32 v254, s3, 35
	v_ashrrev_i32_e32 v1, 6, v0
	v_readlane_b32 s2, v251, 47
	v_readlane_b32 s7, v251, 11
	v_readlane_b32 s8, v251, 12
	v_add_u32_e32 v16, s2, v1
	s_cmp_lt_u32 s2, 64
	s_cselect_b32 s4, 0x4000, 0
	s_cmpk_lg_i32 s90, 0x200
	s_cselect_b32 s4, 0, s4
	s_mov_b32 s30, 0
	v_max_i32_e32 v16, s4, v16
	s_movk_i32 s2, 0x4000
	v_cmp_gt_i32_e32 vcc, s2, v16
	v_readlane_b32 s9, v251, 13
	v_readlane_b32 s10, v251, 14
	v_readlane_b32 s11, v251, 15
	v_readlane_b32 s12, v251, 16
	v_readlane_b32 s13, v251, 17
	v_readlane_b32 s14, v251, 18
	v_readlane_b32 s15, v251, 19
	v_readlane_b32 s16, v251, 20
	v_readlane_b32 s17, v251, 21
	v_readlane_b32 s18, v251, 22
	v_readlane_b32 s19, v251, 23
	s_and_saveexec_b64 s[2:3], vcc
	v_readlane_b32 s6, v254, 23
	v_readlane_b32 s7, v254, 24
	s_cbranch_execz .LBB0_287
	v_readlane_b32 s4, v254, 34
	v_readlane_b32 s5, v254, 35
	v_readlane_b32 s8, v251, 8
	s_lshl_b64 s[4:5], s[4:5], 2
	v_readlane_b32 s14, v251, 14
	v_lshlrev_b32_e32 v0, 2, v0
	v_readlane_b32 s15, v251, 15
	s_add_u32 s4, s14, s4
	v_and_b32_e32 v17, 0xfc, v0
	s_addc_u32 s5, s15, s5
	v_lshlrev_b32_e32 v160, 2, v17
	global_load_dwordx4 v[0:3], v160, s[4:5]
	global_load_dwordx4 v[4:7], v160, s[4:5] offset:1024
	global_load_dwordx4 v[8:11], v160, s[4:5] offset:2048
	global_load_dwordx4 v[12:15], v160, s[4:5] offset:3072
	v_and_b32_e32 v20, 64, v194
	v_add_u32_e32 v20, 64, v20
	v_xor_b32_e32 v21, 32, v194
	v_cmp_lt_i32_e32 vcc, v21, v20
	v_lshl_add_u64 v[18:19], s[46:47], 0, v[160:161]
	v_readlane_b32 s9, v251, 9
	v_cndmask_b32_e32 v21, v194, v21, vcc
	v_lshlrev_b32_e32 v22, 2, v21
	v_xor_b32_e32 v21, 16, v194
	v_cmp_lt_i32_e32 vcc, v21, v20
	v_readlane_b32 s10, v251, 10
	v_readlane_b32 s11, v251, 11
	v_cndmask_b32_e32 v21, v194, v21, vcc
	v_lshlrev_b32_e32 v23, 2, v21
	v_xor_b32_e32 v21, 8, v194
	v_cmp_lt_i32_e32 vcc, v21, v20
	v_readlane_b32 s12, v251, 12
	v_readlane_b32 s13, v251, 13
	v_cndmask_b32_e32 v21, v194, v21, vcc
	v_lshlrev_b32_e32 v24, 2, v21
	v_xor_b32_e32 v21, 4, v194
	v_cmp_lt_i32_e32 vcc, v21, v20
	v_readlane_b32 s16, v251, 16
	v_readlane_b32 s17, v251, 17
	v_cndmask_b32_e32 v21, v194, v21, vcc
	v_lshlrev_b32_e32 v25, 2, v21
	v_xor_b32_e32 v21, 2, v194
	v_cmp_lt_i32_e32 vcc, v21, v20
	v_readlane_b32 s18, v251, 18
	v_readlane_b32 s19, v251, 19
	v_cndmask_b32_e32 v21, v194, v21, vcc
	v_lshlrev_b32_e32 v26, 2, v21
	v_xor_b32_e32 v21, 1, v194
	v_cmp_lt_i32_e32 vcc, v21, v20
	v_readlane_b32 s20, v251, 20
	v_readlane_b32 s21, v251, 21
	v_cndmask_b32_e32 v20, v194, v21, vcc
	v_lshlrev_b32_e32 v27, 2, v20
	v_lshlrev_b32_e32 v20, 1, v17
	v_mov_b32_e32 v21, v161
	v_lshl_add_u64 v[20:21], s[0:1], 0, v[20:21]
	s_mov_b64 s[0:1], 0x2800000
	v_lshl_add_u64 v[20:21], v[20:21], 0, s[0:1]
	s_mov_b64 s[0:1], 0
	v_readlane_b32 s22, v251, 22
	v_readlane_b32 s23, v251, 23

.LBB0_287:
	s_or_b64 exec, exec, s[2:3]
	s_cmp_lg_u32 s30, 0
	s_cbranch_scc1 .Lnx_done
	s_mov_b32 s30, 1
	s_cmpk_lg_i32 s90, 0x200
	s_cbranch_scc1 .Lnx_done
	v_readlane_b32 s31, v251, 47
	s_nop 0
	s_sub_i32 s31, s31, 64
	s_cmp_lt_u32 s31, 0x200
	s_cbranch_scc0 .Lnx_done
	v_ashrrev_i32_e32 v17, 6, v186
	v_add_u32_e32 v17, s31, v17
	v_and_b32_e32 v16, 63, v17
	v_lshrrev_b32_e32 v17, 6, v17
	v_lshl_add_u32 v16, v17, 11, v16
	s_movk_i32 s6, 0x4000
	s_mov_b64 s[0:1], 0
	s_mov_b64 s[2:3], exec
	s_branch .LBB0_286
